# phase-1 gate-column conversion preamble: 16 dependent load round trips replaced by 16 loads in flight with counted waits
# speedup vs baseline: 1.0117x; 1.0002x over previous
; __device__ __forceinline__ unsigned cvt_pk_bf16(float lo, float hi) { unsigned r; asm volatile("v_cvt_pk_bf16_f32 %0, %1, %2" : "=v"(r) : "v"(lo), "v"(hi)); return r; }
; __device__ __forceinline__ void phase_ln_in(const Frame& F) {
;     ...
;     for (int k = F.tid; k < D; k += NTHREADS) { const float* sp = win + (size_t)k * NIN + 9216;
; #pragma unroll
;         for (int q = 0; q < 4; ++q) { const f32x4 v = *(const f32x4*)(sp + 4 * q); const unsigned w01 = cvt_pk_bf16(v[0], v[1]), w23 = cvt_pk_bf16(v[2], v[3]);
;             wgB[(4 * q + 0) * LP + k] = (bf16_t)(w01 & 0xffffu); wgB[(4 * q + 1) * LP + k] = (bf16_t)(w01 >> 16); wgB[(4 * q + 2) * LP + k] = (bf16_t)(w23 & 0xffffu); wgB[(4 * q + 3) * LP + k] = (bf16_t)(w23 >> 16); } }
;     __syncthreads();
.LBB0_145:
	global_load_dwordx4 v[100:103], v[0:1], off
	global_load_dwordx4 v[104:107], v[0:1], off offset:16
	global_load_dwordx4 v[108:111], v[0:1], off offset:32
	global_load_dwordx4 v[112:115], v[0:1], off offset:48
	v_lshl_add_u64 v[0:1], v[0:1], 0, s[6:7]
	global_load_dwordx4 v[116:119], v[0:1], off
	global_load_dwordx4 v[120:123], v[0:1], off offset:16
	global_load_dwordx4 v[124:127], v[0:1], off offset:32
	global_load_dwordx4 v[128:131], v[0:1], off offset:48
	v_lshl_add_u64 v[0:1], v[0:1], 0, s[6:7]
	global_load_dwordx4 v[132:135], v[0:1], off
	global_load_dwordx4 v[136:139], v[0:1], off offset:16
	global_load_dwordx4 v[140:143], v[0:1], off offset:32
	global_load_dwordx4 v[148:151], v[0:1], off offset:48
	v_lshl_add_u64 v[0:1], v[0:1], 0, s[6:7]
	global_load_dwordx4 v[152:155], v[0:1], off
	global_load_dwordx4 v[156:159], v[0:1], off offset:16
	global_load_dwordx4 v[160:163], v[0:1], off offset:32
	global_load_dwordx4 v[164:167], v[0:1], off offset:48
	s_waitcnt vmcnt(15)
	v_cvt_pk_bf16_f32 v8, v100, v101
	v_cvt_pk_bf16_f32 v9, v102, v103
	ds_write_b16 v3, v8 offset:0
	ds_write_b16_d16_hi v3, v8 offset:4128
	ds_write_b16 v3, v9 offset:8256
	ds_write_b16_d16_hi v3, v9 offset:12384
	s_waitcnt vmcnt(14)
	v_cvt_pk_bf16_f32 v8, v104, v105
	v_cvt_pk_bf16_f32 v9, v106, v107
	ds_write_b16 v3, v8 offset:16512
	ds_write_b16_d16_hi v3, v8 offset:20640
	ds_write_b16 v3, v9 offset:24768
	ds_write_b16_d16_hi v3, v9 offset:28896
	s_waitcnt vmcnt(13)
	v_cvt_pk_bf16_f32 v8, v108, v109
	v_cvt_pk_bf16_f32 v9, v110, v111
	ds_write_b16 v3, v8 offset:33024
	ds_write_b16_d16_hi v3, v8 offset:37152
	ds_write_b16 v3, v9 offset:41280
	ds_write_b16_d16_hi v3, v9 offset:45408
	s_waitcnt vmcnt(12)
	v_cvt_pk_bf16_f32 v8, v112, v113
	v_cvt_pk_bf16_f32 v9, v114, v115
	ds_write_b16 v3, v8 offset:49536
	ds_write_b16_d16_hi v3, v8 offset:53664
	ds_write_b16 v3, v9 offset:57792
	ds_write_b16_d16_hi v3, v9 offset:61920
	s_waitcnt vmcnt(11)
	v_cvt_pk_bf16_f32 v8, v116, v117
	v_cvt_pk_bf16_f32 v9, v118, v119
	ds_write_b16 v3, v8 offset:1024
	ds_write_b16_d16_hi v3, v8 offset:5152
	ds_write_b16 v3, v9 offset:9280
	ds_write_b16_d16_hi v3, v9 offset:13408
	s_waitcnt vmcnt(10)
	v_cvt_pk_bf16_f32 v8, v120, v121
	v_cvt_pk_bf16_f32 v9, v122, v123
	ds_write_b16 v3, v8 offset:17536
	ds_write_b16_d16_hi v3, v8 offset:21664
	ds_write_b16 v3, v9 offset:25792
	ds_write_b16_d16_hi v3, v9 offset:29920
	s_waitcnt vmcnt(9)
	v_cvt_pk_bf16_f32 v8, v124, v125
	v_cvt_pk_bf16_f32 v9, v126, v127
	ds_write_b16 v3, v8 offset:34048
	ds_write_b16_d16_hi v3, v8 offset:38176
	ds_write_b16 v3, v9 offset:42304
	ds_write_b16_d16_hi v3, v9 offset:46432
	s_waitcnt vmcnt(8)
	v_cvt_pk_bf16_f32 v8, v128, v129
	v_cvt_pk_bf16_f32 v9, v130, v131
	ds_write_b16 v3, v8 offset:50560
	ds_write_b16_d16_hi v3, v8 offset:54688
	ds_write_b16 v3, v9 offset:58816
	ds_write_b16_d16_hi v3, v9 offset:62944
	s_waitcnt vmcnt(7)
	v_cvt_pk_bf16_f32 v8, v132, v133
	v_cvt_pk_bf16_f32 v9, v134, v135
	ds_write_b16 v3, v8 offset:2048
	ds_write_b16_d16_hi v3, v8 offset:6176
	ds_write_b16 v3, v9 offset:10304
	ds_write_b16_d16_hi v3, v9 offset:14432
	s_waitcnt vmcnt(6)
	v_cvt_pk_bf16_f32 v8, v136, v137
	v_cvt_pk_bf16_f32 v9, v138, v139
	ds_write_b16 v3, v8 offset:18560
	ds_write_b16_d16_hi v3, v8 offset:22688
	ds_write_b16 v3, v9 offset:26816
	ds_write_b16_d16_hi v3, v9 offset:30944
	s_waitcnt vmcnt(5)
	v_cvt_pk_bf16_f32 v8, v140, v141
	v_cvt_pk_bf16_f32 v9, v142, v143
	ds_write_b16 v3, v8 offset:35072
	ds_write_b16_d16_hi v3, v8 offset:39200
	ds_write_b16 v3, v9 offset:43328
	ds_write_b16_d16_hi v3, v9 offset:47456
	s_waitcnt vmcnt(4)
	v_cvt_pk_bf16_f32 v8, v148, v149
	v_cvt_pk_bf16_f32 v9, v150, v151
	ds_write_b16 v3, v8 offset:51584
	ds_write_b16_d16_hi v3, v8 offset:55712
	ds_write_b16 v3, v9 offset:59840
	ds_write_b16_d16_hi v3, v9 offset:63968
	s_waitcnt vmcnt(3)
	v_cvt_pk_bf16_f32 v8, v152, v153
	v_cvt_pk_bf16_f32 v9, v154, v155
	ds_write_b16 v3, v8 offset:3072
	ds_write_b16_d16_hi v3, v8 offset:7200
	ds_write_b16 v3, v9 offset:11328
	ds_write_b16_d16_hi v3, v9 offset:15456
	s_waitcnt vmcnt(2)
	v_cvt_pk_bf16_f32 v8, v156, v157
	v_cvt_pk_bf16_f32 v9, v158, v159
	ds_write_b16 v3, v8 offset:19584
	ds_write_b16_d16_hi v3, v8 offset:23712
	ds_write_b16 v3, v9 offset:27840
	ds_write_b16_d16_hi v3, v9 offset:31968
	s_waitcnt vmcnt(1)
	v_cvt_pk_bf16_f32 v8, v160, v161
	v_cvt_pk_bf16_f32 v9, v162, v163
	ds_write_b16 v3, v8 offset:36096
	ds_write_b16_d16_hi v3, v8 offset:40224
	ds_write_b16 v3, v9 offset:44352
	ds_write_b16_d16_hi v3, v9 offset:48480
	s_waitcnt vmcnt(0)
	v_cvt_pk_bf16_f32 v8, v164, v165
	v_cvt_pk_bf16_f32 v9, v166, v167
	ds_write_b16 v3, v8 offset:52608
	ds_write_b16_d16_hi v3, v8 offset:56736
	ds_write_b16 v3, v9 offset:60864
	ds_write_b16_d16_hi v3, v9 offset:64992
	s_or_b64 exec, exec, s[0:1]
	s_lshl_b32 s2, s94, 3
	s_add_i32 s6, s93, s2
	s_cmp_lt_i32 s6, 0x8400
	s_waitcnt lgkmcnt(0)
	s_barrier
; #define LAS __attribute__((address_space(3)))
; __device__ __forceinline__ unsigned cvt_pk_bf16(float lo, float hi) { unsigned r; asm volatile("v_cvt_pk_bf16_f32 %0, %1, %2" : "=v"(r) : "v"(lo), "v"(hi)); return r; }
; __device__ __forceinline__ f32x4 mfma16(bf16x8 a, bf16x8 b, f32x4 c) { return __builtin_amdgcn_mfma_f32_16x16x32_bf16(a, b, c, 0, 0, 0); }
; __device__ __forceinline__ void phase_ln_in(const Frame& F) {
;     ...
;     const float* MOD = (const float*)(F.ws + WS_MOD); float* GATES = (float*)(F.ws + WS_GATES); bf16_t* U = (bf16_t*)(F.ws + WS_U);
;     const int lane = F.lane, wid = F.wid, fr = lane & 15, fq = lane >> 4;
;     const float bias = (F.tid & 15) < 8 ? F.in[11][F.tid & 15] : F.in[12][(F.tid & 15) - 8];
;     for (int r = F.bid * 8 + wid; r < M; r += F.G * 8) {
;         const float* xr = r < MP ? F.in[0] + (size_t)r * D : F.in[1] + (size_t)(r - MP) * D; const int cd = cond_of_row(r);
;         f32x4 xv[8]; float s = 0.f;
; #pragma unroll
;         for (int j = 0; j < 8; ++j) { xv[j] = *(const f32x4*)(xr + j * 256 + lane * 4); s += (xv[j][0] + xv[j][1]) + (xv[j][2] + xv[j][3]); }
;         const float mu = wave_sum(s) * (1.0f / D); float q = 0.f;
; #pragma unroll
;         for (int j = 0; j < 8; ++j) { xv[j] = xv[j] - mu; q += (xv[j][0] * xv[j][0] + xv[j][1] * xv[j][1]) + (xv[j][2] * xv[j][2] + xv[j][3] * xv[j][3]); }
;         const float rstd = rsqrtf(wave_sum(q) * (1.0f / D) + LN_EPS);
;         const float* sh = MOD + (size_t)cd * MODW; const float* sc = sh + D;
; #pragma unroll
;         for (int j = 0; j < 8; ++j) { const int e = j * 256 + lane * 4; const f32x4 scv = *(const f32x4*)(sc + e), shv = *(const f32x4*)(sh + e);
;             const f32x4 u = xv[j] * rstd * (scv + 1.0f) + shv;
;             u32x2 w; w.x = cvt_pk_bf16(u[0], u[1]); w.y = cvt_pk_bf16(u[2], u[3]); *(u32x2*)(U + (size_t)r * D + e) = w; *(LAS u32x2*)(ub + wid * LP + e) = w; }
;         __syncthreads();
;         f32x4 acc = (f32x4){0.f, 0.f, 0.f, 0.f};
; #pragma unroll
;         for (int kk = 0; kk < 8; ++kk) { const int k0 = 256 * wid + 32 * kk + 8 * fq;
;             const bf16x8 af = *(const LAS bf16x8*)(ub + fr * LP + k0), bfv = *(const LAS bf16x8*)(wgB + fr * LP + k0); acc = mfma16(af, bfv, acc); }
; #pragma unroll
;         for (int i = 0; i < 4; ++i) red[(wid * 16 + 4 * fq + i) * 16 + fr] = acc[i];
	s_cbranch_scc0 .LBB0_155
	v_and_b32_e32 v3, 15, v192
	v_lshlrev_b32_e32 v32, 2, v3
	v_mov_b32_e32 v33, 0
	s_movk_i32 s0, 0xffe0
	v_lshl_add_u64 v[0:1], s[84:85], 0, v[32:33]
	s_mov_b32 s1, -1
	v_lshl_add_u64 v[0:1], v[0:1], 0, s[0:1]
	v_lshl_add_u64 v[4:5], s[82:83], 0, v[32:33]
	v_cmp_gt_u32_e32 vcc, 8, v3
	v_mul_u32_u24_e32 v6, 0x810, v3
	s_add_u32 s3, s66, 0x4000
	v_cndmask_b32_e32 v1, v1, v5, vcc
	v_cndmask_b32_e32 v0, v0, v4, vcc
	global_load_dword v38, v[0:1], off
	v_and_b32_e32 v3, 48, v147
	s_addc_u32 s26, s67, 0
	s_add_i32 s7, 0, 0x10200
	v_lshlrev_b32_e32 v1, 1, v6
	v_lshl_or_b32 v3, s93, 9, v3
	s_add_i32 s8, 0, 0x20400
	v_add3_u32 v40, 0, v1, v3
	v_add_u32_e32 v7, s8, v32
	v_add3_u32 v41, s7, v1, v3
	v_and_b32_e32 v1, 0x70, v192
	v_lshl_add_u32 v42, v1, 2, v7
	v_mbcnt_lo_u32_b32 v1, -1, 0
	v_mbcnt_hi_u32_b32 v1, -1, v1
	v_lshl_add_u32 v3, s93, 10, v7
	v_and_b32_e32 v7, 64, v1
	v_add_u32_e32 v7, 64, v7
	v_xor_b32_e32 v9, 32, v1
	v_cmp_lt_i32_e32 vcc, v9, v7
	v_lshl_add_u64 v[18:19], s[66:67], 0, v[32:33]
	s_mov_b64 s[12:13], 0x244000
	v_cndmask_b32_e32 v9, v1, v9, vcc
	v_lshlrev_b32_e32 v44, 2, v9
	v_xor_b32_e32 v9, 16, v1
	v_cmp_lt_i32_e32 vcc, v9, v7
	s_mul_i32 s0, s93, 0x1020
	v_lshl_add_u64 v[34:35], v[18:19], 0, s[12:13]
	v_cndmask_b32_e32 v9, v1, v9, vcc
	v_lshlrev_b32_e32 v45, 2, v9
	v_xor_b32_e32 v9, 8, v1
	v_cmp_lt_i32_e32 vcc, v9, v7
	v_readlane_b32 s12, v254, 36
	s_add_i32 s0, s7, s0
	v_cndmask_b32_e32 v9, v1, v9, vcc
	v_lshlrev_b32_e32 v46, 2, v9
	v_xor_b32_e32 v9, 4, v1
	v_cmp_lt_i32_e32 vcc, v9, v7
	v_lshlrev_b32_e32 v0, 3, v147
	s_lshl_b32 s10, s92, 3
	v_cndmask_b32_e32 v9, v1, v9, vcc
	v_lshlrev_b32_e32 v47, 2, v9
	v_xor_b32_e32 v9, 2, v1
	v_cmp_lt_i32_e32 vcc, v9, v7
	v_readlane_b32 s13, v254, 37
	s_ashr_i32 s7, s6, 31
	v_cndmask_b32_e32 v9, v1, v9, vcc
	v_lshlrev_b32_e32 v48, 2, v9
	v_xor_b32_e32 v9, 1, v1
	v_cmp_lt_i32_e32 vcc, v9, v7
	v_lshlrev_b32_e32 v2, 2, v147
	v_lshlrev_b32_e32 v4, 4, v147
	v_cndmask_b32_e32 v1, v1, v9, vcc
	v_lshlrev_b32_e32 v49, 2, v1
	v_mov_b32_e32 v1, v33
	v_lshl_add_u64 v[36:37], s[12:13], 0, v[0:1]
	s_ashr_i32 s11, s10, 31
	s_lshl_b64 s[12:13], s[6:7], 13
	v_add_u32_e32 v39, s0, v0
	s_movk_i32 s0, 0x80
	v_and_b32_e32 v5, 0x300, v4
	v_or_b32_e32 v4, 0x100, v2
	v_or_b32_e32 v6, 0x200, v2
	v_or_b32_e32 v8, 0x300, v2
	v_or_b32_e32 v10, 0x400, v2
	v_or_b32_e32 v12, 0x500, v2
	v_or_b32_e32 v14, 0x600, v2
	v_or_b32_e32 v16, 0x700, v2
	s_add_u32 s12, s44, s12
	s_mov_b32 s9, 0
	v_cmp_gt_u32_e64 s[0:1], s0, v192
	v_lshrrev_b32_e32 v43, 4, v192
	s_addc_u32 s13, s45, s13
	s_lshl_b64 s[14:15], s[10:11], 13
	v_lshlrev_b32_e32 v32, 2, v2
	s_movk_i32 s27, 0x1000
	v_mov_b32_e32 v50, 0x3727c5ac
	s_mov_b32 s28, 0x800000
	v_lshlrev_b32_e32 v51, 2, v4
	v_lshlrev_b32_e32 v52, 2, v6
	v_lshlrev_b32_e32 v53, 2, v8
	v_lshlrev_b32_e32 v54, 2, v10
	v_lshlrev_b32_e32 v55, 2, v12
	v_lshlrev_b32_e32 v56, 2, v14
	v_lshlrev_b32_e32 v57, 2, v16
	v_add_u32_e32 v58, v3, v5
	s_branch .LBB0_149
